# MLA attention loop: K/V tile loads as global_load with counted vmcnt waits so both prefetch groups stay in flight (two-tile prefetch distance)
# speedup vs baseline: 1.0018x; 1.0018x over previous
; template <int DKA, int DKB, int DV, int MODE  >
; __device__ __forceinline__ void attn_unit(LAS unsigned char* lds, const AttSrc& s, int q0, float c, float sink_l2, const float* qg, f32x16 (&o)[DV / 32], const int tid) {
;     ...
;     bf16x8 qf[KS];
; #pragma unroll
;     for (int ks = 0; ks < KS; ++ks) qf[ks] = *(const bf16x8*)(s.q + (size_t)qrow * s.qp + 16 * ks + 8 * h);
;     if (MODE == 2) {
;         float ssq = 0.f;
; #pragma unroll
;         for (int ks = 0; ks < KS; ++ks)
; #pragma unroll
;             for (int j = 0; j < 8; ++j) { const float f = bf2f((bf16_t)qf[ks][j]); ssq += f * f; }
;         ssq += __shfl_xor(ssq, 32);
;         const float rs = __builtin_amdgcn_rsqf(ssq / (float)DK + EPS);
; #pragma unroll
;         for (int ks = 0; ks < KS; ++ks)
; #pragma unroll
;             for (int j = 0; j < 8; ++j) qf[ks][j] = (short)f2bf(bf2f((bf16_t)qf[ks][j]) * rs * qg[16 * ks + 8 * h + j]);
;     }
;     if (MODE == 1) {
;         float xq[4][8]; float ssq = 0.f;
; #pragma unroll
;         for (int ks = 0; ks < 4; ++ks)
; #pragma unroll
;             for (int j = 0; j < 8; ++j) { xq[ks][j] = bf2f((bf16_t)qf[ks][j]); ssq += xq[ks][j] * xq[ks][j]; }
;         ssq += __shfl_xor(ssq, 32);
;         const float rs = __builtin_amdgcn_rsqf(ssq * (1.f / 64.f) + EPS);
; #pragma unroll
;         for (int ks = 0; ks < 2; ++ks)
; #pragma unroll
;             for (int j = 0; j < 8; ++j) { const int cidx = 16 * ks + 8 * h + j;
;                 const float a = xq[ks][j] * rs * qg[cidx], bq = xq[ks + 2][j] * rs * qg[cidx + 32];
;                 const f32x2 t = s.qcs[(size_t)qrow * 32 + cidx];
;                 qf[ks][j] = (short)f2bf(a * t.x - bq * t.y); qf[ks + 2][j] = (short)f2bf(a * t.y + bq * t.x); }
;     }
;     if (MODE == 0 && DKB == 32) {
;         float xn[4][8], xp[2][8]; float s1 = 0.f, s2 = 0.f;
; #pragma unroll
;         for (int ks = 0; ks < 4; ++ks)
; #pragma unroll
;             for (int j = 0; j < 8; ++j) { xn[ks][j] = bf2f((bf16_t)qf[ks][j]); s1 += xn[ks][j] * xn[ks][j]; }
; #pragma unroll
;         for (int ks = 0; ks < 2; ++ks)
; #pragma unroll
;             for (int j = 0; j < 8; ++j) { xp[ks][j] = bf2f((bf16_t)qf[4 + ks][j]); s2 += xp[ks][j] * xp[ks][j]; }
;         s1 += __shfl_xor(s1, 32); s2 += __shfl_xor(s2, 32);
;         const float r1 = __builtin_amdgcn_rsqf(s1 * (1.f / 64.f) + EPS), r2 = __builtin_amdgcn_rsqf(s2 * (1.f / 32.f) + EPS);
.LBB0_504:
	s_ashr_i32 s54, s12, 4
	s_and_b32 s69, s12, 15
	s_ashr_i32 s55, s54, 31
	s_mul_i32 s26, s54, 0x600000
	s_mul_hi_i32 s12, s54, 0x600000
	s_add_u32 s26, s27, s26
	s_addc_u32 s12, s33, s12
	s_mul_i32 s36, s69, 0xc0
	s_add_u32 s60, s26, s36
	s_addc_u32 s61, s12, 0
	s_lshl_b64 s[36:37], s[54:55], 23
	s_add_u32 s26, s34, s36
	s_addc_u32 s46, s35, s37
	s_lshl_b32 s12, s69, 8
	s_add_u32 s48, s26, s12
	s_addc_u32 s49, s46, 0
	s_lshl_b64 s[46:47], s[54:55], 24
	s_add_u32 s46, s10, s46
	s_addc_u32 s47, s22, s47
	s_lshl_b64 s[54:55], s[54:55], 18
	s_add_u32 s54, s1, s54
	s_addc_u32 s55, s9, s55
	v_readlane_b32 s26, v254, 37
	s_lshl_b32 s52, s53, 8
	v_add_u32_e32 v161, s52, v223
	v_mov_b32_e32 v2, s26
	v_readlane_b32 s26, v254, 38
	ds_read_b64 v[46:47], v2
	v_or_b32_e32 v162, v161, v222
	v_mov_b32_e32 v2, s26
	v_mov_b64_e32 v[4:5], s[60:61]
	s_movk_i32 s26, 0xc00
	v_mad_i64_i32 v[4:5], s[60:61], v162, s26, v[4:5]
	v_lshlrev_b32_e32 v6, 1, v114
	v_mov_b32_e32 v7, v0
	v_lshl_add_u64 v[4:5], v[4:5], 0, v[6:7]
	ds_read_b64 v[2:3], v2
	flat_load_dwordx4 v[42:45], v[4:5]
	flat_load_dwordx4 v[24:27], v[4:5] offset:32
	flat_load_dwordx4 v[16:19], v[4:5] offset:64
	flat_load_dwordx4 v[8:11], v[4:5] offset:96
	flat_load_dwordx4 v[38:41], v[4:5] offset:128
	flat_load_dwordx4 v[34:37], v[4:5] offset:160
	v_ashrrev_i32_e32 v163, 31, v162
	v_lshlrev_b32_e32 v48, 2, v114
	v_mov_b32_e32 v49, v0
	s_waitcnt lgkmcnt(0)
	v_lshl_add_u64 v[30:31], v[2:3], 0, v[48:49]
	flat_load_dwordx4 v[2:5], v[30:31] offset:192
	s_waitcnt vmcnt(0)
	v_and_b32_e32 v173, 0xffff0000, v42
	v_lshlrev_b32_e32 v172, 16, v42
	v_pk_mul_f32 v[74:75], v[172:173], v[172:173]
	v_and_b32_e32 v177, 0xffff0000, v43
	v_lshlrev_b32_e32 v176, 16, v43
	v_pk_mul_f32 v[42:43], v[176:177], v[176:177]
	v_add_f32_e32 v74, v74, v75
	v_and_b32_e32 v175, 0xffff0000, v44
	v_lshlrev_b32_e32 v174, 16, v44
	v_add_f32_e32 v42, v42, v74
	v_pk_mul_f32 v[76:77], v[174:175], v[174:175]
	v_add_f32_e32 v42, v43, v42
	v_and_b32_e32 v179, 0xffff0000, v45
	v_lshlrev_b32_e32 v178, 16, v45
	v_add_f32_e32 v42, v76, v42
	v_pk_mul_f32 v[44:45], v[178:179], v[178:179]
	v_add_f32_e32 v42, v77, v42
	v_and_b32_e32 v111, 0xffff0000, v24
	v_lshlrev_b32_e32 v110, 16, v24
	v_add_f32_e32 v42, v44, v42
	v_pk_mul_f32 v[66:67], v[110:111], v[110:111]
	v_add_f32_e32 v42, v45, v42
	v_and_b32_e32 v169, 0xffff0000, v25
	v_lshlrev_b32_e32 v168, 16, v25
	v_add_f32_e32 v42, v66, v42
	v_pk_mul_f32 v[68:69], v[168:169], v[168:169]
	v_add_f32_e32 v42, v67, v42
	v_and_b32_e32 v113, 0xffff0000, v26
	v_lshlrev_b32_e32 v112, 16, v26
	v_add_f32_e32 v42, v68, v42
	v_pk_mul_f32 v[70:71], v[112:113], v[112:113]
	v_add_f32_e32 v42, v69, v42
	v_and_b32_e32 v171, 0xffff0000, v27
	v_lshlrev_b32_e32 v170, 16, v27
	v_add_f32_e32 v42, v70, v42
	v_pk_mul_f32 v[72:73], v[170:171], v[170:171]
	v_add_f32_e32 v42, v71, v42
	v_and_b32_e32 v99, 0xffff0000, v16
	v_lshlrev_b32_e32 v98, 16, v16
	v_add_f32_e32 v42, v72, v42
	v_pk_mul_f32 v[58:59], v[98:99], v[98:99]
	v_add_f32_e32 v42, v73, v42
	v_and_b32_e32 v165, 0xffff0000, v17
	v_lshlrev_b32_e32 v164, 16, v17
	v_add_f32_e32 v42, v58, v42
	v_pk_mul_f32 v[60:61], v[164:165], v[164:165]
	v_add_f32_e32 v42, v59, v42
	v_and_b32_e32 v101, 0xffff0000, v18
	v_lshlrev_b32_e32 v100, 16, v18
	v_add_f32_e32 v42, v60, v42
	v_pk_mul_f32 v[62:63], v[100:101], v[100:101]
	v_add_f32_e32 v42, v61, v42
	v_and_b32_e32 v167, 0xffff0000, v19
	v_lshlrev_b32_e32 v166, 16, v19
	v_add_f32_e32 v42, v62, v42
	v_pk_mul_f32 v[64:65], v[166:167], v[166:167]
	v_add_f32_e32 v42, v63, v42
	v_and_b32_e32 v103, 0xffff0000, v8
	v_lshlrev_b32_e32 v102, 16, v8
	v_add_f32_e32 v42, v64, v42
	v_pk_mul_f32 v[50:51], v[102:103], v[102:103]
	v_add_f32_e32 v42, v65, v42
	v_and_b32_e32 v107, 0xffff0000, v9
	v_lshlrev_b32_e32 v106, 16, v9
	v_add_f32_e32 v42, v50, v42
	v_pk_mul_f32 v[52:53], v[106:107], v[106:107]
	v_add_f32_e32 v42, v51, v42
	v_and_b32_e32 v105, 0xffff0000, v10
	v_lshlrev_b32_e32 v104, 16, v10
	v_add_f32_e32 v42, v52, v42
	v_pk_mul_f32 v[54:55], v[104:105], v[104:105]
	v_add_f32_e32 v42, v53, v42
	v_and_b32_e32 v109, 0xffff0000, v11
	v_lshlrev_b32_e32 v108, 16, v11
	v_add_f32_e32 v42, v54, v42
	v_pk_mul_f32 v[56:57], v[108:109], v[108:109]
	v_add_f32_e32 v42, v55, v42
	v_add_f32_e32 v42, v56, v42
	v_add_f32_e32 v197, v57, v42
	v_lshlrev_b64 v[42:43], 7, v[162:163]
	v_lshl_add_u64 v[42:43], s[54:55], 0, v[42:43]
	v_lshlrev_b32_e32 v44, 3, v114
	v_mov_b32_e32 v45, v0
	v_lshl_add_u64 v[54:55], v[46:47], 0, v[48:49]
	v_lshl_add_u64 v[56:57], v[42:43], 0, v[44:45]
	flat_load_dwordx4 v[6:9], v[30:31] offset:208
	flat_load_dwordx4 v[10:13], v[30:31] offset:128
	flat_load_dwordx4 v[22:25], v[30:31] offset:80
	flat_load_dwordx4 v[14:17], v[30:31] offset:144
	flat_load_dwordx4 v[18:21], v[30:31] offset:64
	flat_load_dwordx4 v[26:29], v[30:31]
	flat_load_dwordx4 v[42:45], v[56:57]
	v_and_b32_e32 v83, 0xffff0000, v38
	flat_load_dwordx4 v[30:33], v[30:31] offset:16
	s_nop 0
	flat_load_dwordx4 v[62:65], v[54:55]
	flat_load_dwordx4 v[58:61], v[54:55] offset:64
	flat_load_dwordx4 v[46:49], v[56:57] offset:16
	flat_load_dwordx4 v[50:53], v[56:57] offset:32
	flat_load_dwordx4 v[90:93], v[54:55] offset:16
	flat_load_dwordx4 v[94:97], v[54:55] offset:80
	s_nop 0
	flat_load_dwordx4 v[54:57], v[56:57] offset:48
	v_lshlrev_b32_e32 v82, 16, v38
	v_pk_mul_f32 v[68:69], v[82:83], v[82:83]
	v_and_b32_e32 v181, 0xffff0000, v39
	v_lshlrev_b32_e32 v180, 16, v39
	v_pk_mul_f32 v[72:73], v[180:181], v[180:181]
	v_add_f32_e32 v68, v68, v69
	v_and_b32_e32 v85, 0xffff0000, v34
	v_lshlrev_b32_e32 v84, 16, v34
	v_and_b32_e32 v183, 0xffff0000, v35
	v_lshlrev_b32_e32 v182, 16, v35
	v_and_b32_e32 v35, 0xffff0000, v40
	v_lshlrev_b32_e32 v34, 16, v40
	v_add_f32_e32 v68, v72, v68
	v_pk_mul_f32 v[76:77], v[34:35], v[34:35]
	v_add_f32_e32 v68, v73, v68
	v_and_b32_e32 v185, 0xffff0000, v41
	v_lshlrev_b32_e32 v184, 16, v41
	v_add_f32_e32 v68, v76, v68
	v_pk_mul_f32 v[78:79], v[184:185], v[184:185]
	v_add_f32_e32 v68, v77, v68
	v_add_f32_e32 v68, v78, v68
	v_pk_mul_f32 v[66:67], v[84:85], v[84:85]
	v_add_f32_e32 v68, v79, v68
	v_add_f32_e32 v66, v66, v68
	v_pk_mul_f32 v[70:71], v[182:183], v[182:183]
	v_add_f32_e32 v66, v67, v66
	v_and_b32_e32 v39, 0xffff0000, v36
	v_lshlrev_b32_e32 v38, 16, v36
	v_add_f32_e32 v66, v70, v66
	v_pk_mul_f32 v[74:75], v[38:39], v[38:39]
	v_add_f32_e32 v66, v71, v66
	v_and_b32_e32 v41, 0xffff0000, v37
	v_lshlrev_b32_e32 v40, 16, v37
	v_add_f32_e32 v66, v74, v66
	v_pk_mul_f32 v[36:37], v[40:41], v[40:41]
	v_add_f32_e32 v66, v75, v66
	v_add_f32_e32 v36, v36, v66
	v_add_f32_e32 v163, v37, v36
	ds_bpermute_b32 v198, v190, v197
	ds_bpermute_b32 v199, v190, v163
	v_mov_b32_e32 v69, 0
	v_mov_b32_e32 v68, v69
	v_mov_b32_e32 v67, v69
	v_mov_b32_e32 v66, v69
	s_and_saveexec_b64 s[54:55], s[38:39]
	s_cbranch_execz .LBB0_510
; template <int DKA, int DKB, int DV, int MODE  >
; __device__ __forceinline__ void attn_unit(LAS unsigned char* lds, const AttSrc& s, int q0, float c, float sink_l2, const float* qg, f32x16 (&o)[DV / 32], const int tid) {
;     ...
;     ATT_LOAD(krA, vrA, t_lo);
;     if (PF2) { if (t_lo + 1 < t_hi) ATT_LOAD(krB, vrB, t_lo + 1); }
	s_and_saveexec_b64 s[60:61], s[40:41]
	s_xor_b64 s[62:63], exec, s[60:61]
	v_lshl_add_u64 v[36:37], s[46:47], 0, v[122:123]
	v_lshl_add_u64 v[36:37], v[120:121], 1, v[36:37]
	s_mov_b64 s[60:61], 0x580
	v_lshl_add_u64 v[36:37], v[36:37], 0, s[60:61]
	s_andn2_saveexec_b64 s[62:63], s[62:63]
	v_lshl_add_u64 v[36:37], s[48:49], 0, v[124:125]
	v_lshl_add_u64 v[36:37], v[126:127], 1, v[36:37]
	s_or_b64 exec, exec, s[62:63]
	global_load_dwordx4 v[66:69], v[36:37], off
.LBB0_510:
	s_or_b64 exec, exec, s[54:55]
	v_mov_b32_e32 v73, 0
	v_mov_b32_e32 v72, v73
	v_mov_b32_e32 v71, v73
	v_mov_b32_e32 v70, v73
	s_and_saveexec_b64 s[54:55], s[42:43]
	s_cbranch_execz .LBB0_516
	s_and_saveexec_b64 s[60:61], s[44:45]
	s_xor_b64 s[62:63], exec, s[60:61]
	v_lshl_add_u64 v[36:37], s[46:47], 0, v[132:133]
	v_lshl_add_u64 v[36:37], v[130:131], 1, v[36:37]
	s_mov_b64 s[60:61], 0x580
	v_lshl_add_u64 v[36:37], v[36:37], 0, s[60:61]
	s_andn2_saveexec_b64 s[62:63], s[62:63]
	v_lshl_add_u64 v[36:37], s[48:49], 0, v[134:135]
	v_lshl_add_u64 v[36:37], v[136:137], 1, v[36:37]
	s_or_b64 exec, exec, s[62:63]
	global_load_dwordx4 v[70:73], v[36:37], off
.LBB0_516:
	s_or_b64 exec, exec, s[54:55]
	v_lshl_add_u64 v[36:37], s[48:49], 0, v[138:139]
	v_lshl_add_u64 v[36:37], v[140:141], 1, v[36:37]
	global_load_dwordx4 v[86:89], v[36:37], off offset:128
	s_and_saveexec_b64 s[54:55], s[38:39]
	s_cbranch_execz .LBB0_522
	s_and_saveexec_b64 s[60:61], s[40:41]
	s_xor_b64 s[62:63], exec, s[60:61]
	v_lshl_add_u64 v[36:37], s[46:47], 0, v[142:143]
	v_lshl_add_u64 v[36:37], v[120:121], 1, v[36:37]
	s_mov_b64 s[60:61], 0x580
	v_lshl_add_u64 v[36:37], v[36:37], 0, s[60:61]
	s_andn2_saveexec_b64 s[62:63], s[62:63]
	v_lshl_add_u64 v[36:37], s[48:49], 0, v[144:145]
	v_lshl_add_u64 v[36:37], v[126:127], 1, v[36:37]
	s_or_b64 exec, exec, s[62:63]
	global_load_dwordx4 v[74:77], v[36:37], off
.LBB0_522:
	s_or_b64 exec, exec, s[54:55]
	s_and_saveexec_b64 s[54:55], s[42:43]
	s_cbranch_execz .LBB0_528
	s_and_saveexec_b64 s[60:61], s[44:45]
	s_xor_b64 s[62:63], exec, s[60:61]
	v_lshl_add_u64 v[36:37], s[46:47], 0, v[146:147]
	v_lshl_add_u64 v[36:37], v[130:131], 1, v[36:37]
	s_mov_b64 s[60:61], 0x580
	v_lshl_add_u64 v[36:37], v[36:37], 0, s[60:61]
	s_andn2_saveexec_b64 s[62:63], s[62:63]
	v_lshl_add_u64 v[36:37], s[48:49], 0, v[148:149]
	v_lshl_add_u64 v[36:37], v[136:137], 1, v[36:37]
	s_or_b64 exec, exec, s[62:63]
	global_load_dwordx4 v[78:81], v[36:37], off
; __device__ __forceinline__ bf16_t f2bf(float f) { return (bf16_t)(cvt_pk_bf16(f, 0.f) & 0xffffu); }
; template <int DKA, int DKB, int DV, int MODE  >
; __device__ __forceinline__ void attn_unit(LAS unsigned char* lds, const AttSrc& s, int q0, float c, float sink_l2, const float* qg, f32x16 (&o)[DV / 32], const int tid) {
;     ...
; #pragma unroll
;         for (int ks = 0; ks < 4; ++ks)
; #pragma unroll
;             for (int j = 0; j < 8; ++j) qf[ks][j] = (short)f2bf(xn[ks][j] * r1 * qg[16 * ks + 8 * h + j]);
; #pragma unroll
;         for (int j = 0; j < 8; ++j) { const int cidx = 8 * h + j;
;             const float a = xp[0][j] * r2 * s.qg2[cidx], bq = xp[1][j] * r2 * s.qg2[cidx + 16];
;             const f32x2 t = s.qcs[(size_t)qrow * 16 + cidx];
;             qf[4][j] = (short)f2bf(a * t.x - bq * t.y); qf[5][j] = (short)f2bf(a * t.y + bq * t.x); }
;     }
;     const int t_lo = MODE == 1 ? (q0 >= 128 ? q0 / 64 - 2 : 0) : 0;
;     const int t_hi = MODE == 2 ? s.SK / 64 : q0 / 64 + 4;
;     float m = MODE == 1 ? sink_l2 : -INFINITY;
;     float l = (MODE == 1 && h == 0) ? 1.f : 0.f;
; #pragma unroll
;     for (int d = 0; d < DV / 32; ++d)
; #pragma unroll
;         for (int i = 0; i < 16; ++i) o[d][i] = 0.f;
.LBB0_528:
	s_or_b64 exec, exec, s[54:55]
	s_waitcnt vmcnt(0) lgkmcnt(0)
	v_mov_b32_e32 v36, v42
	v_mov_b32_e32 v42, v46
	v_add_f32_e32 v46, v163, v199
	v_fmamk_f32 v46, v46, 0x3d000000, v238
	v_rsq_f32_e32 v46, v46
	v_mov_b32_e32 v200, v50
	v_mov_b32_e32 v201, v52
	v_mov_b32_e32 v52, v51
	v_pk_mul_f32 v[50:51], v[46:47], v[82:83] op_sel_hi:[0,1]
	v_pk_mul_f32 v[50:51], v[50:51], v[62:63]
	v_pk_mul_f32 v[62:63], v[46:47], v[84:85] op_sel_hi:[0,1]
	v_mov_b32_e32 v37, v44
	v_mov_b32_e32 v44, v43
	v_pk_mul_f32 v[58:59], v[62:63], v[58:59]
	v_mov_b32_e32 v43, v48
	v_pk_mul_f32 v[62:63], v[58:59], v[44:45]
	v_mov_b32_e32 v48, v47
	v_pk_fma_f32 v[62:63], v[50:51], v[36:37], v[62:63] neg_lo:[0,0,1] neg_hi:[0,0,1]
	v_pk_mul_f32 v[38:39], v[46:47], v[38:39] op_sel_hi:[0,1]
	v_cvt_pk_bf16_f32 v82, v62, v63
	v_pk_mul_f32 v[62:63], v[46:47], v[180:181] op_sel_hi:[0,1]
	v_pk_mul_f32 v[62:63], v[62:63], v[64:65]
	v_pk_mul_f32 v[64:65], v[46:47], v[182:183] op_sel_hi:[0,1]
	v_pk_mul_f32 v[60:61], v[64:65], v[60:61]
	v_pk_mul_f32 v[34:35], v[46:47], v[34:35] op_sel_hi:[0,1]
	v_pk_mul_f32 v[64:65], v[60:61], v[48:49]
	v_pk_mul_f32 v[38:39], v[38:39], v[94:95]
	v_pk_fma_f32 v[64:65], v[62:63], v[42:43], v[64:65] neg_lo:[0,0,1] neg_hi:[0,0,1]
	v_pk_mul_f32 v[34:35], v[34:35], v[90:91]
	v_cvt_pk_bf16_f32 v83, v64, v65
	v_pk_mul_f32 v[64:65], v[38:39], v[52:53]
	v_pk_mul_f32 v[40:41], v[46:47], v[40:41] op_sel_hi:[0,1]
	v_pk_fma_f32 v[64:65], v[34:35], v[200:201], v[64:65] neg_lo:[0,0,1] neg_hi:[0,0,1]
	v_pk_mul_f32 v[40:41], v[40:41], v[96:97]
	v_cvt_pk_bf16_f32 v84, v64, v65
	v_pk_mul_f32 v[64:65], v[46:47], v[184:185] op_sel_hi:[0,1]
	v_mov_b32_e32 v46, v54
	v_add_f32_e32 v54, v197, v198
	v_fmamk_f32 v54, v54, 0x3c800000, v238
	v_rsq_f32_e32 v54, v54
	v_mov_b32_e32 v47, v56
	v_mov_b32_e32 v56, v55
	v_pk_mul_f32 v[64:65], v[64:65], v[92:93]
	v_pk_mul_f32 v[90:91], v[40:41], v[56:57]
	s_lshl_b32 s53, s53, 2
	v_pk_fma_f32 v[90:91], v[64:65], v[46:47], v[90:91] neg_lo:[0,0,1] neg_hi:[0,0,1]
	s_add_i32 s53, s53, 4
	v_cvt_pk_bf16_f32 v85, v90, v91
	v_pk_mul_f32 v[90:91], v[54:55], v[172:173] op_sel_hi:[0,1]
	v_pk_mul_f32 v[26:27], v[26:27], v[90:91]
	v_or_b32_e32 v163, 31, v161
	v_cvt_pk_bf16_f32 v90, v26, v27
	v_pk_mul_f32 v[26:27], v[54:55], v[176:177] op_sel_hi:[0,1]
	v_pk_mul_f32 v[26:27], v[28:29], v[26:27]
	v_lshl_add_u64 v[172:173], v[158:159], 0, s[36:37]
	v_cvt_pk_bf16_f32 v91, v26, v27
	v_pk_mul_f32 v[26:27], v[54:55], v[174:175] op_sel_hi:[0,1]
	v_pk_mul_f32 v[26:27], v[30:31], v[26:27]
	v_mov_b32_e32 v174, 0
	v_cvt_pk_bf16_f32 v92, v26, v27
	v_pk_mul_f32 v[26:27], v[54:55], v[178:179] op_sel_hi:[0,1]
	v_pk_mul_f32 v[26:27], v[32:33], v[26:27]
	v_mov_b32_e32 v175, 0xff800000
	v_cvt_pk_bf16_f32 v93, v26, v27
	v_pk_mul_f32 v[26:27], v[54:55], v[110:111] op_sel_hi:[0,1]
	v_pk_mul_f32 v[18:19], v[18:19], v[26:27]
	s_mov_b32 s72, 0
	v_cvt_pk_bf16_f32 v94, v18, v19
	v_pk_mul_f32 v[18:19], v[54:55], v[168:169] op_sel_hi:[0,1]
	v_pk_mul_f32 v[18:19], v[20:21], v[18:19]
	v_lshl_add_u64 v[168:169], v[154:155], 0, s[36:37]
	v_cvt_pk_bf16_f32 v95, v18, v19
	v_pk_mul_f32 v[18:19], v[54:55], v[112:113] op_sel_hi:[0,1]
	v_pk_mul_f32 v[18:19], v[22:23], v[18:19]
	s_mov_b32 s62, 3
	v_cvt_pk_bf16_f32 v96, v18, v19
	v_pk_mul_f32 v[18:19], v[54:55], v[170:171] op_sel_hi:[0,1]
	v_pk_mul_f32 v[18:19], v[24:25], v[18:19]
	v_lshl_add_u64 v[170:171], v[156:157], 0, s[36:37]
	v_cvt_pk_bf16_f32 v97, v18, v19
	v_pk_mul_f32 v[18:19], v[54:55], v[98:99] op_sel_hi:[0,1]
	v_pk_mul_f32 v[10:11], v[10:11], v[18:19]
	v_lshl_add_u64 v[18:19], s[48:49], 0, v[150:151]
	v_lshl_add_u64 v[18:19], v[140:141], 1, v[18:19]
	global_load_dwordx4 v[110:113], v[18:19], off offset:128
	v_cvt_pk_bf16_f32 v98, v10, v11
	v_pk_mul_f32 v[10:11], v[54:55], v[164:165] op_sel_hi:[0,1]
	v_pk_mul_f32 v[10:11], v[12:13], v[10:11]
	v_lshl_add_u64 v[164:165], v[120:121], 1, s[46:47]
	v_cvt_pk_bf16_f32 v99, v10, v11
	v_pk_mul_f32 v[10:11], v[54:55], v[100:101] op_sel_hi:[0,1]
	v_pk_mul_f32 v[10:11], v[14:15], v[10:11]
	s_movk_i32 s63, 0x7f
	v_cvt_pk_bf16_f32 v100, v10, v11
	v_pk_mul_f32 v[10:11], v[54:55], v[166:167] op_sel_hi:[0,1]
	v_pk_mul_f32 v[10:11], v[16:17], v[10:11]
	v_lshl_add_u64 v[166:167], v[130:131], 1, s[46:47]
	v_cvt_pk_bf16_f32 v101, v10, v11
	v_pk_mul_f32 v[10:11], v[54:55], v[102:103] op_sel_hi:[0,1]
	v_pk_mul_f32 v[2:3], v[2:3], v[10:11]
	v_mov_b32_e32 v18, 0
	v_cvt_pk_bf16_f32 v102, v2, v3
	v_pk_mul_f32 v[2:3], v[54:55], v[106:107] op_sel_hi:[0,1]
	v_pk_mul_f32 v[2:3], v[4:5], v[2:3]
	v_mov_b32_e32 v19, v174
	v_cvt_pk_bf16_f32 v103, v2, v3
	v_pk_mul_f32 v[2:3], v[54:55], v[104:105] op_sel_hi:[0,1]
	v_pk_mul_f32 v[2:3], v[6:7], v[2:3]
	v_mov_b32_e32 v20, v174
	v_cvt_pk_bf16_f32 v104, v2, v3
	v_pk_mul_f32 v[2:3], v[54:55], v[108:109] op_sel_hi:[0,1]
	v_pk_mul_f32 v[2:3], v[8:9], v[2:3]
	v_mov_b32_e32 v21, v174
	v_cvt_pk_bf16_f32 v105, v2, v3
	v_pk_mul_f32 v[2:3], v[58:59], v[36:37]
	v_mov_b32_e32 v22, v174
	v_pk_fma_f32 v[2:3], v[50:51], v[44:45], v[2:3]
	v_mov_b32_e32 v23, v174
	v_cvt_pk_bf16_f32 v106, v2, v3
	v_pk_mul_f32 v[2:3], v[60:61], v[42:43]
	v_mov_b32_e32 v24, v174
	v_pk_fma_f32 v[2:3], v[62:63], v[48:49], v[2:3]
	v_mov_b32_e32 v25, v174
	v_cvt_pk_bf16_f32 v107, v2, v3
	v_pk_mul_f32 v[2:3], v[38:39], v[200:201]
	v_mov_b32_e32 v26, v174
	v_pk_fma_f32 v[2:3], v[34:35], v[52:53], v[2:3]
	v_mov_b32_e32 v27, v174
	v_cvt_pk_bf16_f32 v108, v2, v3
	v_pk_mul_f32 v[2:3], v[40:41], v[46:47]
	v_mov_b32_e32 v28, v174
	v_pk_fma_f32 v[2:3], v[64:65], v[56:57], v[2:3]
	v_mov_b32_e32 v29, v174
	v_cvt_pk_bf16_f32 v109, v2, v3
	v_mov_b32_e32 v30, v174
	v_mov_b32_e32 v31, v174
	v_mov_b32_e32 v32, v174
	v_mov_b32_e32 v33, v174
	v_mov_b32_e32 v2, v174
	v_mov_b32_e32 v3, v174
	v_mov_b32_e32 v4, v174
	v_mov_b32_e32 v5, v174
	v_mov_b32_e32 v6, v174
	v_mov_b32_e32 v7, v174
	v_mov_b32_e32 v8, v174
	v_mov_b32_e32 v9, v174
	v_mov_b32_e32 v10, v174
	v_mov_b32_e32 v11, v174
	v_mov_b32_e32 v12, v174
	v_mov_b32_e32 v13, v174
	v_mov_b32_e32 v14, v174
	v_mov_b32_e32 v15, v174
	v_mov_b32_e32 v16, v174
	v_mov_b32_e32 v17, v174
	s_and_saveexec_b64 s[46:47], s[38:39]
	s_cbranch_execz .LBB0_531
	s_branch .LBB0_530
.LBB0_529:
	s_mov_b32 s72, s70
	s_add_i32 s26, s62, -2
	s_cmp_ge_u32 s26, s53
	s_cbranch_scc1 .Lw1_full
	s_waitcnt vmcnt(2)
	s_branch .Lw1_done

; #define LAS __attribute__((address_space(3)))
; template <int DKA, int DKB, int DV, int MODE  >
; __device__ __forceinline__ void attn_unit(LAS unsigned char* lds, const AttSrc& s, int q0, float c, float sink_l2, const float* qg, f32x16 (&o)[DV / 32], const int tid) {
;     ...
;             LAS unsigned char* Kl = lds + (PF2 ? 0 : ((t - t_lo) & 1)) * TB; LAS unsigned char* Vl = Kl + KBYTES;
;             ATT_STORE(krA, vrA, Kl, Vl);
;             __syncthreads();
;             if (t + STEP < t_hi) ATT_LOAD(krA, vrA, t + STEP);
.Lw1_done:
	s_and_saveexec_b64 s[46:47], s[38:39]
	s_cbranch_execz .LBB0_531
.LBB0_530:
	v_add_u32_e32 v34, v192, v193
	s_waitcnt lgkmcnt(0)
	ds_write_b128 v34, v[66:69]
.LBB0_531:
	s_or_b64 exec, exec, s[46:47]
	s_and_saveexec_b64 s[46:47], s[42:43]
	s_cbranch_execz .LBB0_533
	v_add_u32_e32 v34, v194, v195
	s_waitcnt lgkmcnt(0)
	ds_write_b128 v34, v[70:73]
.LBB0_533:
	s_or_b64 exec, exec, s[46:47]
	s_add_i32 s70, s72, 2
	s_add_i32 s71, s62, -1
	s_cmp_ge_u32 s71, s53
	s_waitcnt lgkmcnt(0)
	ds_write_b128 v196, v[86:89] offset:13312
	s_waitcnt lgkmcnt(0)
	s_barrier
	s_cbranch_scc1 .LBB0_548
	s_lshl_b32 s54, s70, 6
	s_and_saveexec_b64 s[46:47], s[38:39]
	s_cbranch_execz .LBB0_540
	s_and_saveexec_b64 s[48:49], s[40:41]
	s_xor_b64 s[48:49], exec, s[48:49]
	v_add_u32_e32 v34, s54, v118
	v_ashrrev_i32_e32 v35, 31, v34
	v_lshlrev_b64 v[34:35], 13, v[34:35]
	v_lshl_add_u64 v[34:35], v[164:165], 0, v[34:35]
	s_mov_b64 s[60:61], 0x580
	v_lshl_add_u64 v[34:35], v[34:35], 0, s[60:61]
	s_andn2_saveexec_b64 s[48:49], s[48:49]
	v_lshl_add_u64 v[34:35], v[168:169], 0, s[12:13]
	s_mov_b64 s[60:61], 0x1d080000
	v_lshl_add_u64 v[34:35], v[34:35], 0, s[60:61]
	s_or_b64 exec, exec, s[48:49]
	global_load_dwordx4 v[66:69], v[34:35], off
.LBB0_540:
	s_or_b64 exec, exec, s[46:47]
	s_and_saveexec_b64 s[46:47], s[42:43]
	s_cbranch_execz .LBB0_546
	s_and_saveexec_b64 s[48:49], s[44:45]
	s_xor_b64 s[48:49], exec, s[48:49]
	v_add_u32_e32 v34, s54, v128
	v_ashrrev_i32_e32 v35, 31, v34
	v_lshlrev_b64 v[34:35], 13, v[34:35]
	v_lshl_add_u64 v[34:35], v[166:167], 0, v[34:35]
	s_mov_b64 s[54:55], 0x580
	v_lshl_add_u64 v[34:35], v[34:35], 0, s[54:55]
	s_andn2_saveexec_b64 s[48:49], s[48:49]
	v_lshl_add_u64 v[34:35], v[170:171], 0, s[12:13]
	s_mov_b64 s[54:55], 0x1d080000
	v_lshl_add_u64 v[34:35], v[34:35], 0, s[54:55]
	s_or_b64 exec, exec, s[48:49]
	global_load_dwordx4 v[70:73], v[34:35], off
.LBB0_546:
	s_or_b64 exec, exec, s[46:47]
	v_lshl_add_u64 v[34:35], v[172:173], 0, s[12:13]
	v_add_co_u32_e32 v34, vcc, 0x1d080000, v34
	s_nop 1
	v_addc_co_u32_e32 v35, vcc, 0, v35, vcc
	global_load_dwordx4 v[86:89], v[34:35], off offset:128
	s_add_i32 s26, s63, 0xffffff81
	v_cmp_le_i32_e32 vcc, s26, v163
	s_and_saveexec_b64 s[54:55], vcc
	s_cbranch_execnz .LBB0_549

; #define LAS __attribute__((address_space(3)))
; template <int DKA, int DKB, int DV, int MODE  >
; __device__ __forceinline__ void attn_unit(LAS unsigned char* lds, const AttSrc& s, int q0, float c, float sink_l2, const float* qg, f32x16 (&o)[DV / 32], const int tid) {
;     ...
;         if (PF2) { if (t + 1 < t_hi) {
;             LAS unsigned char* Kl = lds + TB; LAS unsigned char* Vl = Kl + KBYTES;
;             ATT_STORE(krB, vrB, Kl, Vl);
.LBB0_550:
	s_cmp_ge_u32 s71, s53
	s_cbranch_scc1 .Lw2_full
	s_waitcnt vmcnt(2)
	s_branch .Lw2_done

; #define LAS __attribute__((address_space(3)))
; template <int DKA, int DKB, int DV, int MODE  >
; __device__ __forceinline__ void attn_unit(LAS unsigned char* lds, const AttSrc& s, int q0, float c, float sink_l2, const float* qg, f32x16 (&o)[DV / 32], const int tid) {
;     ...
;             LAS unsigned char* Kl = lds + TB; LAS unsigned char* Vl = Kl + KBYTES;
;             ATT_STORE(krB, vrB, Kl, Vl);
;             __syncthreads();
;             if (t + 3 < t_hi) ATT_LOAD(krB, vrB, t + 3);
.Lw2_done:
	s_and_saveexec_b64 s[46:47], s[38:39]
	v_add_u32_e32 v34, v192, v193
	ds_write_b128 v34, v[74:77] offset:22528
	s_or_b64 exec, exec, s[46:47]
	s_and_saveexec_b64 s[46:47], s[42:43]
	v_add_u32_e32 v34, v194, v195
	ds_write_b128 v34, v[78:81] offset:22528
	s_or_b64 exec, exec, s[46:47]
	s_cmp_ge_u32 s62, s53
	ds_write_b128 v196, v[110:113] offset:35840
	s_waitcnt lgkmcnt(0)
	s_barrier
	s_cbranch_scc1 .LBB0_568
	s_lshl_b32 s54, s72, 6
	s_addk_i32 s54, 0xc0
	s_and_saveexec_b64 s[46:47], s[38:39]
	s_cbranch_execz .LBB0_561
	s_and_saveexec_b64 s[48:49], s[40:41]
	s_xor_b64 s[48:49], exec, s[48:49]
	v_add_u32_e32 v34, s54, v118
	v_ashrrev_i32_e32 v35, 31, v34
	v_lshlrev_b64 v[34:35], 13, v[34:35]
	v_lshl_add_u64 v[34:35], v[164:165], 0, v[34:35]
	s_mov_b64 s[60:61], 0x580
	v_lshl_add_u64 v[34:35], v[34:35], 0, s[60:61]
	s_andn2_saveexec_b64 s[48:49], s[48:49]
	v_lshl_add_u64 v[34:35], v[168:169], 0, s[12:13]
	s_mov_b64 s[60:61], 0x1d0c0000
	v_lshl_add_u64 v[34:35], v[34:35], 0, s[60:61]
	s_or_b64 exec, exec, s[48:49]
	global_load_dwordx4 v[74:77], v[34:35], off
.LBB0_561:
	s_or_b64 exec, exec, s[46:47]
	s_and_saveexec_b64 s[46:47], s[42:43]
	s_cbranch_execz .LBB0_567
	s_and_saveexec_b64 s[48:49], s[44:45]
	s_xor_b64 s[48:49], exec, s[48:49]
	v_add_u32_e32 v34, s54, v128
	v_ashrrev_i32_e32 v35, 31, v34
	v_lshlrev_b64 v[34:35], 13, v[34:35]
	v_lshl_add_u64 v[34:35], v[166:167], 0, v[34:35]
	s_mov_b64 s[54:55], 0x580
	v_lshl_add_u64 v[34:35], v[34:35], 0, s[54:55]
	s_andn2_saveexec_b64 s[48:49], s[48:49]
	v_lshl_add_u64 v[34:35], v[170:171], 0, s[12:13]
	s_mov_b64 s[54:55], 0x1d0c0000
	v_lshl_add_u64 v[34:35], v[34:35], 0, s[54:55]
	s_or_b64 exec, exec, s[48:49]
	global_load_dwordx4 v[78:81], v[34:35], off
.LBB0_567:
	s_or_b64 exec, exec, s[46:47]
	v_lshl_add_u64 v[34:35], v[172:173], 0, s[12:13]
	v_add_co_u32_e32 v34, vcc, 0x1d0c0000, v34
	s_nop 1
	v_addc_co_u32_e32 v35, vcc, 0, v35, vcc
	global_load_dwordx4 v[110:113], v[34:35], off offset:128
